# XCD-local P3->P4: P4 rows remapped to the producing XCC, barrier 4 = XCC-local arrival counter when placement is round-robin (fallback otherwise)
# speedup vs baseline: 1.0091x; 1.0091x over previous
; __device__ __forceinline__ unsigned xb_ld(unsigned* p)              { return __hip_atomic_load(p, __ATOMIC_RELAXED, __HIP_MEMORY_SCOPE_AGENT); }
; __device__ __forceinline__ unsigned xb_add(unsigned* p, unsigned v) { return __hip_atomic_fetch_add(p, v, __ATOMIC_RELAXED, __HIP_MEMORY_SCOPE_AGENT); }
; #define XB_SPIN(cond, bar) do { unsigned _sp = 0; while (cond) { __builtin_amdgcn_s_sleep(1); \
;     if ((++_sp & 255u) == 0u) { if (xb_ld(&(bar)[XB_TMO])) break; if (_sp > XB_SPIN_CAP) { atomicAdd(&(bar)[XB_TMO], 1u); break; } } } } while (0)
; __device__ __forceinline__ void xcd_barrier(const XcdBarrier& b) {
;     asm volatile("s_waitcnt vmcnt(0)" ::: "memory");
;     __syncthreads();
;     if (threadIdx.x == 0) {
;         unsigned* bar = b.bar;
;         __builtin_amdgcn_s_waitcnt(0);
;         unsigned nloc = b.st[0], nx = b.st[1];
;         if (nloc == 0u) { xcd_barrier_complete(bar, b.x, nloc, nx); b.st[0] = nloc; b.st[1] = nx; }
;         const unsigned old = xb_add(&bar[XB_XSUB(b.x)], 1u);
;         const unsigned gen = old / nloc;
;         if (old + 1u == (gen + 1u) * nloc) {
;             __builtin_amdgcn_fence(__ATOMIC_RELEASE, "agent");
;             asm volatile("s_waitcnt vmcnt(0)" ::: "memory");
;             const unsigned og = xb_add(&bar[XB_TOP], 1u);
;             const unsigned tg = og / nx;
;             if (og + 1u == (tg + 1u) * nx) xb_add(&bar[XB_TOPGEN], 1u);
;             else XB_SPIN(xb_ld(&bar[XB_TOPGEN]) == tg, bar);
;             __builtin_amdgcn_fence(__ATOMIC_ACQUIRE, "agent");
;             xb_add(&bar[XB_XGEN(b.x)], 1u);
;             asm volatile("s_waitcnt vmcnt(0)" ::: "memory");
;         } else {
;             XB_SPIN(xb_ld(&bar[XB_XGEN(b.x)]) == gen, bar);
;             __builtin_amdgcn_fence(__ATOMIC_ACQUIRE, "agent");
;             asm volatile("s_waitcnt vmcnt(0)" ::: "memory");
;         }
.LBB0_133:
	s_cmp_lt_i32 s27, 3
	s_cbranch_scc1 .LBB0_183
	s_waitcnt vmcnt(0) lgkmcnt(0)
	s_barrier
	v_cmp_eq_u32_e32 vcc, 0, v0
	s_and_saveexec_b64 s[0:1], vcc
	s_cbranch_execz .Lgb1_join
	s_and_b32 s4, s2, 7
	s_sub_u32 s4, s4, s84
	s_sub_u32 s5, s3, 0x100
	s_or_b32 s4, s4, s5
	s_cmp_eq_u32 s4, 0
	s_cbranch_scc1 .Lgb1_rr
	v_mov_b32_e32 v1, 0x3404
	v_mov_b32_e32 v2, 1
	global_store_dword v1, v2, s[22:23]
	s_waitcnt vmcnt(0)
.Lgb1_rr:
	v_mov_b32_e32 v1, s85
	ds_read_b32 v2, v1
	ds_read_b32 v3, v1 offset:4
	s_waitcnt lgkmcnt(0)
	v_readfirstlane_b32 s6, v2
	v_readfirstlane_b32 s7, v3
	s_nop 3
	s_lshl_b32 s4, s84, 8
	s_add_u32 s4, s22, s4
	s_addc_u32 s5, s23, 0
	v_mov_b32_e32 v4, 0x1000
	v_mov_b32_e32 v5, 1
	global_atomic_add v5, v4, v5, s[4:5] offset:1024 sc0
	s_mul_i32 s14, s6, 2
	s_add_i32 s14, s14, -1
	s_mul_i32 s7, s7, 2
	v_mov_b32_e32 v3, 0x3400
	v_mov_b32_e32 v2, 1
	s_waitcnt vmcnt(0)
	v_readfirstlane_b32 s15, v5
	s_nop 3
	s_cmp_lg_u32 s15, s14
	s_cbranch_scc1 .Lgb1_poll
	buffer_wbl2 sc1
	s_waitcnt vmcnt(0)
	global_atomic_add v3, v2, s[22:23]

; __device__ __forceinline__ unsigned xb_ld(unsigned* p)              { return __hip_atomic_load(p, __ATOMIC_RELAXED, __HIP_MEMORY_SCOPE_AGENT); }
; __device__ __forceinline__ unsigned xb_add(unsigned* p, unsigned v) { return __hip_atomic_fetch_add(p, v, __ATOMIC_RELAXED, __HIP_MEMORY_SCOPE_AGENT); }
; #define XB_SPIN(cond, bar) do { unsigned _sp = 0; while (cond) { __builtin_amdgcn_s_sleep(1); \
;     if ((++_sp & 255u) == 0u) { if (xb_ld(&(bar)[XB_TMO])) break; if (_sp > XB_SPIN_CAP) { atomicAdd(&(bar)[XB_TMO], 1u); break; } } } } while (0)
; __device__ __forceinline__ void xcd_barrier(const XcdBarrier& b) {
;     ...
;             const unsigned og = xb_add(&bar[XB_TOP], 1u);
;             const unsigned tg = og / nx;
;             if (og + 1u == (tg + 1u) * nx) xb_add(&bar[XB_TOPGEN], 1u);
;             else XB_SPIN(xb_ld(&bar[XB_TOPGEN]) == tg, bar);
;             __builtin_amdgcn_fence(__ATOMIC_ACQUIRE, "agent");
;             xb_add(&bar[XB_XGEN(b.x)], 1u);
;             asm volatile("s_waitcnt vmcnt(0)" ::: "memory");
;         } else {
;             XB_SPIN(xb_ld(&bar[XB_XGEN(b.x)]) == gen, bar);
;             __builtin_amdgcn_fence(__ATOMIC_ACQUIRE, "agent");
;             asm volatile("s_waitcnt vmcnt(0)" ::: "memory");
;         }
.Lgb1_spin:
	global_load_dwordx2 v[4:5], v3, s[22:23] sc1
	s_waitcnt vmcnt(0)
	v_readfirstlane_b32 s15, v4
	s_nop 3
	s_cmp_ge_u32 s15, s7
	s_cbranch_scc1 .Lgb1_acq
	s_sleep 1
	s_add_i32 s11, s11, 1
	s_cmp_lt_u32 s11, 0x8000
	s_cbranch_scc1 .Lgb1_spin
.Lgb1_acq:
	buffer_inv sc1
	s_waitcnt vmcnt(0)
	ds_write_b32 v1, v5 offset:12
	s_waitcnt lgkmcnt(0)

; __device__ __forceinline__ unsigned xb_ld(unsigned* p)              { return __hip_atomic_load(p, __ATOMIC_RELAXED, __HIP_MEMORY_SCOPE_AGENT); }
; __device__ __forceinline__ unsigned xb_add(unsigned* p, unsigned v) { return __hip_atomic_fetch_add(p, v, __ATOMIC_RELAXED, __HIP_MEMORY_SCOPE_AGENT); }
; #define XB_SPIN(cond, bar) do { unsigned _sp = 0; while (cond) { __builtin_amdgcn_s_sleep(1); \
;     if ((++_sp & 255u) == 0u) { if (xb_ld(&(bar)[XB_TMO])) break; if (_sp > XB_SPIN_CAP) { atomicAdd(&(bar)[XB_TMO], 1u); break; } } } } while (0)
; __device__ __forceinline__ void xcd_barrier(const XcdBarrier& b) {
;     asm volatile("s_waitcnt vmcnt(0)" ::: "memory");
;     __syncthreads();
;     if (threadIdx.x == 0) {
;         unsigned* bar = b.bar;
;         __builtin_amdgcn_s_waitcnt(0);
;         unsigned nloc = b.st[0], nx = b.st[1];
;         if (nloc == 0u) { xcd_barrier_complete(bar, b.x, nloc, nx); b.st[0] = nloc; b.st[1] = nx; }
;         const unsigned old = xb_add(&bar[XB_XSUB(b.x)], 1u);
;         const unsigned gen = old / nloc;
;         if (old + 1u == (gen + 1u) * nloc) {
;             __builtin_amdgcn_fence(__ATOMIC_RELEASE, "agent");
;             asm volatile("s_waitcnt vmcnt(0)" ::: "memory");
;             const unsigned og = xb_add(&bar[XB_TOP], 1u);
;             const unsigned tg = og / nx;
;             if (og + 1u == (tg + 1u) * nx) xb_add(&bar[XB_TOPGEN], 1u);
;             else XB_SPIN(xb_ld(&bar[XB_TOPGEN]) == tg, bar);
;             __builtin_amdgcn_fence(__ATOMIC_ACQUIRE, "agent");
;             xb_add(&bar[XB_XGEN(b.x)], 1u);
;             asm volatile("s_waitcnt vmcnt(0)" ::: "memory");
;         } else {
;             XB_SPIN(xb_ld(&bar[XB_XGEN(b.x)]) == gen, bar);
;             __builtin_amdgcn_fence(__ATOMIC_ACQUIRE, "agent");
;             asm volatile("s_waitcnt vmcnt(0)" ::: "memory");
;         }
.LBB0_787:
	s_waitcnt vmcnt(0) lgkmcnt(0)
	s_barrier
	v_cmp_eq_u32_e32 vcc, 0, v0
	s_and_saveexec_b64 s[0:1], vcc
	s_cbranch_execz .Lgb4_join
	v_mov_b32_e32 v1, s85
	ds_read_b32 v2, v1
	ds_read_b32 v3, v1 offset:4
	ds_read_b32 v4, v1 offset:12
	s_waitcnt lgkmcnt(0)
	v_readfirstlane_b32 s6, v2
	v_readfirstlane_b32 s7, v3
	v_readfirstlane_b32 s14, v4
	s_nop 3
	s_cmp_eq_u32 s14, 0
	s_cbranch_scc0 .Lgb4_global
	s_lshl_b32 s4, s84, 7
	s_addk_i32 s4, 0x3800
	v_mov_b32_e32 v4, s4
	v_mov_b32_e32 v5, 1
	global_atomic_add v4, v5, s[22:23]
	s_mov_b32 s11, 0
.Lgb4_lspin:
	global_load_dword v5, v4, s[22:23] sc1
	s_waitcnt vmcnt(0)
	v_readfirstlane_b32 s15, v5
	s_nop 3
	s_cmp_ge_u32 s15, 32
	s_cbranch_scc1 .Lgb4_acq
	s_sleep 1
	s_add_i32 s11, s11, 1
	s_cmp_lt_u32 s11, 0x8000
	s_cbranch_scc1 .Lgb4_lspin
	s_branch .Lgb4_acq
.Lgb4_global:
	s_lshl_b32 s4, s84, 8
	s_add_u32 s4, s22, s4
	s_addc_u32 s5, s23, 0
	v_mov_b32_e32 v4, 0x1000
	v_mov_b32_e32 v5, 1
	global_atomic_add v5, v4, v5, s[4:5] offset:1024 sc0
	s_mul_i32 s14, s6, 5
	s_add_i32 s14, s14, -1
	s_mul_i32 s7, s7, 5
	v_mov_b32_e32 v3, 0x3400
	v_mov_b32_e32 v2, 1
	s_waitcnt vmcnt(0)
	v_readfirstlane_b32 s15, v5
	s_nop 3
	s_cmp_lg_u32 s15, s14
	s_cbranch_scc1 .Lgb4_poll
	buffer_wbl2 sc1
	s_waitcnt vmcnt(0)
	global_atomic_add v3, v2, s[22:23]

; __global__ void __launch_bounds__(NTHR, 2) mk_fwd(Args a) {
;     ...
;         const int gw = bx * NWAVES + wave, NGW = G * NWAVES;
;         f32x4 gv[8];
; #pragma unroll
;         for (int j = 0; j < 8; ++j) gv[j] = ((const f32x4*)norm_post)[lane + 64 * j];
;         for (int m0 = gw; m0 < NTOK; m0 += 2 * NGW) {
;             f32x4 xv[2][8]; u32x2 ov[2][8]; float part[2];
; #pragma unroll
;             for (int r = 0; r < 2; ++r) { const int m = m0 + r * NGW; const bool ok = m < NTOK; const int mm = ok ? m : m0;
;                 part[r] = (lane < 32) ? OSS[(size_t)mm * 32 + lane] : 0.f;
.LBB0_836:
	s_cmp_gt_i32 s26, 5
	s_cselect_b64 s[0:1], -1, 0
	s_cmp_lt_i32 s27, 6
	s_cselect_b64 s[4:5], -1, 0
	s_or_b64 s[0:1], s[0:1], s[4:5]
	s_and_b64 vcc, exec, s[0:1]
	s_cbranch_vccnz .LBB0_846
	v_mov_b32_e32 v32, s85
	ds_read_b32 v32, v32 offset:12
	s_lshl_b32 s0, s2, 3
	s_add_i32 s4, s33, s0
	s_movk_i32 s20, 0x4000
	s_lshl_b32 s21, s3, 3
	s_waitcnt lgkmcnt(0)
	v_readfirstlane_b32 s0, v32
	s_nop 3
	s_cmp_eq_u32 s0, 0
	s_cbranch_scc0 .Lp4_map
	s_and_b32 s0, s2, 7
	s_lshl_b32 s0, s0, 11
	s_and_b32 s4, s2, 0xfffffff8
	s_add_i32 s4, s4, s33
	s_add_i32 s4, s4, s0
	s_add_i32 s20, s0, 0x800
	s_movk_i32 s21, 0x100
.Lp4_map:
	s_cmp_ge_i32 s4, s20
	s_cbranch_scc1 .LBB0_846
	v_lshlrev_b32_e32 v32, 4, v255
	v_mov_b32_e32 v33, 0
	v_lshl_add_u64 v[0:1], s[48:49], 0, v[32:33]
	s_waitcnt vmcnt(0)
	v_add_co_u32_e32 v34, vcc, 0x1000, v0
	s_mov_b32 s14, s21
	s_nop 0
	v_addc_co_u32_e32 v35, vcc, 0, v1, vcc
	global_load_dwordx4 v[0:3], v[34:35], off offset:3072
	s_waitcnt lgkmcnt(0)
	global_load_dwordx4 v[4:7], v[34:35], off offset:2048
	global_load_dwordx4 v[8:11], v[34:35], off offset:1024
	global_load_dwordx4 v[12:15], v[34:35], off
	global_load_dwordx4 v[16:19], v32, s[48:49] offset:3072
	global_load_dwordx4 v[20:23], v32, s[48:49] offset:2048
	global_load_dwordx4 v[24:27], v32, s[48:49] offset:1024
	global_load_dwordx4 v[28:31], v32, s[48:49]
	v_lshlrev_b32_e32 v34, 3, v255
	v_mov_b32_e32 v35, v33
	v_lshl_add_u64 v[98:99], s[30:31], 0, v[34:35]
	v_lshlrev_b32_e32 v34, 2, v255
	v_lshl_add_u64 v[100:101], s[12:13], 0, v[34:35]
	v_mbcnt_lo_u32_b32 v34, -1, 0
	v_mbcnt_hi_u32_b32 v34, -1, v34
	v_and_b32_e32 v35, 64, v34
	v_add_u32_e32 v35, 64, v35
	v_xor_b32_e32 v36, 1, v34
	v_cmp_lt_i32_e32 vcc, v36, v35
	s_movk_i32 s15, 0x1000
	v_cmp_gt_u32_e64 s[0:1], 32, v255
	v_cndmask_b32_e32 v36, v34, v36, vcc
	v_lshlrev_b32_e32 v136, 2, v36
	v_xor_b32_e32 v36, 2, v34
	v_cmp_lt_i32_e32 vcc, v36, v35
	v_lshl_add_u64 v[96:97], s[52:53], 0, v[32:33]
	v_lshl_add_u64 v[102:103], s[50:51], 0, v[32:33]
	v_cndmask_b32_e32 v36, v34, v36, vcc
	v_lshlrev_b32_e32 v137, 2, v36
	v_xor_b32_e32 v36, 4, v34
	v_cmp_lt_i32_e32 vcc, v36, v35
	s_lshl_b32 s16, s21, 1
	v_mov_b32_e32 v142, 0x358637bd
	v_cndmask_b32_e32 v36, v34, v36, vcc
	v_lshlrev_b32_e32 v138, 2, v36
	v_xor_b32_e32 v36, 8, v34
	v_cmp_lt_i32_e32 vcc, v36, v35
	s_mov_b32 s17, 0xf800000
	v_mov_b32_e32 v143, 0x260
	v_cndmask_b32_e32 v36, v34, v36, vcc
	v_lshlrev_b32_e32 v139, 2, v36
	v_xor_b32_e32 v36, 16, v34
	v_cmp_lt_i32_e32 vcc, v36, v35
	s_nop 1
	v_cndmask_b32_e32 v36, v34, v36, vcc
	v_lshlrev_b32_e32 v140, 2, v36
	v_xor_b32_e32 v36, 32, v34
	v_cmp_lt_i32_e32 vcc, v36, v35
	s_nop 1
	v_cndmask_b32_e32 v34, v34, v36, vcc
	v_lshlrev_b32_e32 v141, 2, v34
	s_branch .LBB0_840
.LBB0_839:
	s_add_i32 s4, s4, s16
	s_cmp_lt_i32 s4, s20
	s_cbranch_scc0 .LBB0_846

; __global__ void __launch_bounds__(NTHR, 2) mk_fwd(Args a) {
;     ...
;         for (int m0 = gw; m0 < NTOK; m0 += 2 * NGW) {
;             f32x4 xv[2][8]; u32x2 ov[2][8]; float part[2];
; #pragma unroll
;             for (int r = 0; r < 2; ++r) { const int m = m0 + r * NGW; const bool ok = m < NTOK; const int mm = ok ? m : m0;
;                 part[r] = (lane < 32) ? OSS[(size_t)mm * 32 + lane] : 0.f;
;                 const f32x4* xr = (const f32x4*)(x + (size_t)mm * DMODEL) + lane; const u32x2* ob = (const u32x2*)(OutB + (size_t)mm * DMODEL) + lane;
; #pragma unroll
;                 for (int j = 0; j < 8; ++j) { xv[r][j] = __builtin_nontemporal_load(xr + 64 * j); ov[r][j] = __builtin_nontemporal_load(ob + 64 * j); } }
.LBB0_842:
	s_or_b64 exec, exec, s[2:3]
	s_lshl_b64 s[10:11], s[4:5], 13
	v_lshl_add_u64 v[34:35], v[96:97], 0, s[10:11]
	s_lshl_b64 s[2:3], s[4:5], 12
	v_lshl_add_u64 v[36:37], v[98:99], 0, s[2:3]
	global_load_dwordx4 v[92:95], v[34:35], off nt
	global_load_dwordx4 v[88:91], v[34:35], off offset:1024 nt
	global_load_dwordx4 v[84:87], v[34:35], off offset:2048 nt
	global_load_dwordx4 v[80:83], v[34:35], off offset:3072 nt
	global_load_dwordx2 v[134:135], v[36:37], off nt
	global_load_dwordx2 v[132:133], v[36:37], off offset:512 nt
	global_load_dwordx2 v[130:131], v[36:37], off offset:1024 nt
	global_load_dwordx2 v[128:129], v[36:37], off offset:1536 nt
	v_add_co_u32_e32 v34, vcc, 0x1000, v34
	s_add_i32 s6, s14, s4
	s_nop 0
	v_addc_co_u32_e32 v35, vcc, 0, v35, vcc
	global_load_dwordx4 v[76:79], v[34:35], off nt
	global_load_dwordx4 v[72:75], v[34:35], off offset:1024 nt
	global_load_dwordx4 v[68:71], v[34:35], off offset:2048 nt
	s_waitcnt lgkmcnt(0)
	global_load_dwordx4 v[60:63], v[34:35], off offset:3072 nt
	global_load_dwordx2 v[126:127], v[36:37], off offset:2048 nt
	global_load_dwordx2 v[124:125], v[36:37], off offset:2560 nt
	global_load_dwordx2 v[122:123], v[36:37], off offset:3072 nt
	global_load_dwordx2 v[118:119], v[36:37], off offset:3584 nt
	s_cmp_lt_i32 s6, s20
	s_cselect_b64 s[8:9], -1, 0
	s_and_b64 s[2:3], s[8:9], exec
	s_cselect_b32 s2, s6, s4
	s_ashr_i32 s3, s2, 31
	v_mov_b32_e32 v144, 0
	s_and_saveexec_b64 s[12:13], s[0:1]
	s_cbranch_execz .LBB0_844
	s_lshl_b64 s[18:19], s[2:3], 7
	v_lshl_add_u64 v[34:35], v[100:101], 0, s[18:19]
	global_load_dword v144, v[34:35], off
